# epiwide_e1: E1 GEMM epilogue also widened to dwordx4 stores via v_permlane16_swap (plus O1)
# speedup vs baseline: 1.0111x; 1.0052x over previous
;   __host__ __device__ __forceinline__ float* G() const { return (float*)(wsl() + OFF_G); }
; #define PG8_STAGE(bufoff, gbase, voff) do { _Pragma("unroll") for (int _i = 0; _i < 2; ++_i) \
;         __builtin_amdgcn_global_load_lds((const unsigned*)((const char*)(gbase) + (voff)[_i]), (PG8_LAS unsigned*)(lds + (bufoff) + ldsw + _i * 8192), 16, 0, 0); } while (0)
; #define PG8_WAIT_V(n) asm volatile("s_waitcnt vmcnt(" #n ")" ::: "memory")
; #define PG8_BAR __builtin_amdgcn_s_barrier()
;   __device__ bool next(int i, Unit& u) const {
;     const long L = (long)i * G + c; if (L >= nwg) return false;
;     int wgid = (int)L; { const int q = nwg / NXCD, r = nwg % NXCD, xcd = wgid % NXCD, off = wgid / NXCD; wgid = (xcd < r ? xcd * (q + 1) : r * (q + 1) + (xcd - r) * q) + off; }
;     const int nig = WGM * nN, gid = wgid / nig, fm = gid * WGM, gsz = (nM - fm) < WGM ? (nM - fm) : WGM;
;     int pm = fm + ((wgid % nig) % gsz); u.pn = (wgid % nig) / gsz;
;     if (latent) pm = pm + 1 + (pm >= 32 ? 1 : 0);
;     u.pm = pm; return true;
;   }
; template <class Epi>
; __device__ __forceinline__ void gemm_phase(PG8_LAS unsigned char* lds, const Gemm g, const Sched& S, const Epi& E) {
;     ...
;     Unit cur, nxt; int ui = 0;
;     if (!S.next(0, cur)) return;
;     f32x4 acc[2][2][4][2];
; #pragma unroll
;     for (int a = 0; a < 2; ++a)
; #pragma unroll
;         for (int b = 0; b < 2; ++b)
; #pragma unroll
;             for (int m = 0; m < 4; ++m)
; #pragma unroll
;                 for (int n = 0; n < 2; ++n) acc[a][b][m][n] = (f32x4){0.f, 0.f, 0.f, 0.f};
;     bf16x8 At[4][2], B0[2][2], B1[2][2];
;     const char* cA = (const char*)g.A + (size_t)cur.pm * tsA; const char* cB = (const char*)g.Bt + (size_t)cur.pn * tsB;
;     PG8_STAGE(PG8_SB(0, 0), cB, voffB); PG8_STAGE(PG8_SA(0, 0), cA, voffA); PG8_STAGE(PG8_SB(0, 1), cB + hsB, voffB); PG8_STAGE(PG8_SA(0, 1), cA + hsA, voffA);
;     if (wr == 1) PG8_BAR;
;     PG8_WAIT_V(4); PG8_BAR;
;     PG8_STAGE(PG8_SB(1, 0), cB + kstep, voffB); PG8_STAGE(PG8_SA(1, 0), cA + kstep, voffA); PG8_STAGE(PG8_SB(1, 1), cB + hsB + kstep, voffB);
;     PG8_WAIT_V(6); PG8_BAR;
;     for (;;) {
;         const bool has_next = S.next(ui + 1, nxt);
;         const char* nA = has_next ? (const char*)g.A + (size_t)nxt.pm * tsA : cA; const char* nB = has_next ? (const char*)g.Bt + (size_t)nxt.pn * tsB : cB;
.LBB0_790:
	s_add_u32 s44, s10, 0x7290000
	s_addc_u32 s45, s11, 0
	v_bfe_u32 v16, v9, 4, 2
	s_add_u32 s46, s10, 0x11186000
	v_and_b32_e32 v15, 15, v9
	v_lshlrev_b32_e32 v17, 4, v16
	v_lshlrev_b32_e32 v9, 2, v9
	s_addc_u32 s47, s11, 0
	v_lshl_or_b32 v138, s2, 6, v15
	v_lshl_or_b32 v15, v15, 6, v17
	s_lshl_b32 s2, s2, 13
	v_and_b32_e32 v9, 32, v9
	v_bitop3_b32 v17, v15, s2, v9 bitop3:0xde
	s_lshl_b32 s2, s3, 5
	s_and_b32 s23, s2, 0x60
	s_add_i32 m0, s19, 0x18000
	v_lshl_add_u64 v[6:7], v[6:7], 0, s[76:77]
	s_lshl_b32 s2, s23, 7
	s_waitcnt vmcnt(4)
	s_barrier
	global_load_lds_dwordx4 v[6:7], off
	v_lshl_add_u64 v[4:5], v[4:5], 0, s[76:77]
	s_add_i32 m0, s19, 0x1a000
	s_add_i32 s24, s19, 0x8000
	s_add_i32 s25, s19, 0xa000
	v_bitop3_b32 v139, v15, s2, v9 bitop3:0xde
	global_load_lds_dwordx4 v[4:5], off
	v_lshl_add_u64 v[2:3], v[2:3], 0, s[76:77]
	s_mov_b32 m0, s24
	s_add_u32 s2, s8, 0x40080
	global_load_lds_dwordx4 v[2:3], off
	v_lshl_add_u64 v[0:1], v[0:1], 0, s[76:77]
	s_mov_b32 m0, s25
	s_addc_u32 s3, s9, 0
	global_load_lds_dwordx4 v[0:1], off
	s_add_i32 m0, s19, 0x1c000
	v_lshl_add_u64 v[0:1], s[2:3], 0, v[166:167]
	global_load_lds_dwordx4 v[0:1], off
	v_lshl_add_u64 v[0:1], s[2:3], 0, v[128:129]
	s_add_i32 m0, s19, 0x1e000
	v_lshlrev_b32_e32 v140, 2, v16
	global_load_lds_dwordx4 v[0:1], off
	v_lshlrev_b32_e32 v0, 14, v8
	v_and_b32_e32 v0, 0xffff8000, v0
	v_lshl_add_u32 v0, v10, 11, v0
	v_and_b32_e32 v1, 1, v8
	v_lshl_or_b32 v0, v1, 6, v0
	v_lshl_add_u32 v130, v11, 1, v0
	v_lshlrev_b32_e32 v0, 14, v12
	v_and_b32_e32 v0, 0xffff8000, v0
	s_waitcnt vmcnt(6)
	v_lshl_add_u32 v0, v13, 11, v0
	v_and_b32_e32 v1, 1, v12
	v_lshl_or_b32 v0, v1, 6, v0
	v_or_b32_e32 v141, 16, v138
	v_or_b32_e32 v142, 32, v138
	v_or_b32_e32 v143, 48, v138
	v_add_u32_e32 v144, 0x80, v138
	v_add_u32_e32 v145, 0x90, v138
	v_add_u32_e32 v146, 0xa0, v138
	v_add_u32_e32 v147, 0xb0, v138
	s_ashr_i32 s26, s12, 31
	v_mov_b32_e32 v131, v167
	v_lshl_add_u32 v132, v14, 1, v0
	v_mov_b32_e32 v133, v167
	s_mov_b32 s27, 0
	v_add_u32_e32 v148, 0, v17
	s_barrier
	s_branch .LBB0_792
.LBB0_792:
	s_add_i32 s27, s27, 1
	s_mul_i32 s2, s27, s33
	s_mul_hi_u32 s3, s27, s80
	s_add_i32 s3, s3, s2
	s_mul_i32 s2, s27, s80
	s_add_u32 s10, s2, s12
	s_addc_u32 s11, s3, s26
	v_mov_b64_e32 v[0:1], 0x2d5
	v_cmp_gt_i64_e64 s[40:41], s[10:11], v[0:1]
	s_and_b64 vcc, exec, s[40:41]
	s_cbranch_vccnz .LBB0_798
	s_ashr_i32 s2, s10, 31
	s_lshr_b32 s2, s2, 29
	s_add_i32 s5, s10, s2
	s_and_b32 s2, s5, -8
	s_sub_i32 s29, s10, s2
	s_cmp_gt_i32 s29, 5
	s_mov_b64 s[2:3], -1
	s_cbranch_scc0 .LBB0_795
	s_mul_i32 s2, s29, 0x5a
	s_add_i32 s30, s2, 6
	s_mov_b64 s[2:3], 0

; #define PG8_STAGE(bufoff, gbase, voff) do { _Pragma("unroll") for (int _i = 0; _i < 2; ++_i) \
;         __builtin_amdgcn_global_load_lds((const unsigned*)((const char*)(gbase) + (voff)[_i]), (PG8_LAS unsigned*)(lds + (bufoff) + ldsw + _i * 8192), 16, 0, 0); } while (0)
; #define PG8_LDA(dst, b, h) do { _Pragma("unroll") for (int m = 0; m < 4; ++m) _Pragma("unroll") for (int k = 0; k < 2; ++k) dst[m][k] = *(const PG8_LAS bf16x8*)(lds + PG8_SA(b, h) + aoff + m * 2048 + k * 1024); } while (0)
; #define PG8_LDB(dst, b, h) do { _Pragma("unroll") for (int n = 0; n < 2; ++n) _Pragma("unroll") for (int k = 0; k < 2; ++k) dst[n][k] = *(const PG8_LAS bf16x8*)(lds + PG8_SB(b, h) + boff + n * 2048 + k * 1024); } while (0)
; #define PG8_MMA(ai, bj, At, Bt) do { __builtin_amdgcn_s_setprio(1); _Pragma("unroll") for (int m = 0; m < 4; ++m) _Pragma("unroll") for (int n = 0; n < 2; ++n) _Pragma("unroll") for (int k = 0; k < 2; ++k) \
;         acc[ai][bj][m][n] = __builtin_amdgcn_mfma_f32_16x16x32_bf16(Bt[n][k], At[m][k], acc[ai][bj][m][n], 0, 0, 0); __builtin_amdgcn_s_setprio(0); } while (0)
; #define PG8_WAIT_V(n) asm volatile("s_waitcnt vmcnt(" #n ")" ::: "memory")
; #define PG8_WAIT_L(n) asm volatile("s_waitcnt lgkmcnt(" #n ")" ::: "memory")
; #define PG8_BAR __builtin_amdgcn_s_barrier()
; #define PG8_SCHED __builtin_amdgcn_sched_barrier(0)
; template <class Epi>
; __device__ __forceinline__ void gemm_phase(PG8_LAS unsigned char* lds, const Gemm g, const Sched& S, const Epi& E) {
;     ...
;             PG8_LDB(B0, 0, 0); PG8_SCHED; PG8_LDA(At, 0, 0); PG8_STAGE(PG8_SA(1, 1), a1 + hsA, voffA);
;             PG8_WAIT_L(8); PG8_BAR; PG8_WAIT_L(0); PG8_MMA(0, 0, At, B0); PG8_BAR; PG8_SCHED;
;             PG8_LDB(B1, 0, 1); PG8_STAGE(PG8_SB(0, 0), b2, voffB);
;             PG8_BAR; PG8_WAIT_L(0); PG8_MMA(0, 1, At, B1); PG8_BAR;
;             PG8_LDA(At, 0, 1); PG8_STAGE(PG8_SA(0, 0), a2, voffA);
;             PG8_BAR; PG8_WAIT_L(0); PG8_MMA(1, 0, At, B0); PG8_BAR; PG8_SCHED;
;             PG8_STAGE(PG8_SB(0, 1), b2 + hsB, voffB);
;             PG8_WAIT_V(6); PG8_BAR; PG8_MMA(1, 1, At, B1); PG8_BAR;
.LBB0_799:
	s_add_u32 s8, s6, 0xfffc0080
	s_addc_u32 s9, s7, -1
	s_add_i32 s38, 0, 0x10000
	v_add_u32_e32 v149, s38, v139
	ds_read_b128 v[134:137], v149
	ds_read_b128 v[150:153], v149 offset:1024
	ds_read_b128 v[154:157], v149 offset:2048
	ds_read_b128 v[158:161], v149 offset:3072
	s_cmp_eq_u32 s37, 12
	s_cselect_b32 s11, s2, s9
	s_cselect_b32 s10, s3, s8
	s_cselect_b32 s9, s5, s36
	s_cselect_b32 s8, s29, s30
	v_lshl_add_u64 v[162:163], s[6:7], 0, v[130:131]
	s_add_i32 m0, s19, 0xc000
	ds_read_b128 v[178:181], v148
	ds_read_b128 v[182:185], v148 offset:1024
	ds_read_b128 v[186:189], v148 offset:2048
	ds_read_b128 v[190:193], v148 offset:3072
	ds_read_b128 v[194:197], v148 offset:4096
	ds_read_b128 v[198:201], v148 offset:5120
	ds_read_b128 v[202:205], v148 offset:6144
	ds_read_b128 v[206:209], v148 offset:7168
	global_load_lds_dwordx4 v[162:163], off
	v_lshl_add_u64 v[162:163], s[6:7], 0, v[132:133]
	s_add_i32 m0, s19, 0xe000
	s_nop 0
	global_load_lds_dwordx4 v[162:163], off
	s_waitcnt lgkmcnt(8)
	s_barrier
	s_waitcnt lgkmcnt(0)
	s_setprio 1
	s_waitcnt lgkmcnt(0)
	v_mfma_f32_16x16x32_bf16 v[124:127], v[134:137], v[178:181], v[124:127]
	v_mfma_f32_16x16x32_bf16 v[120:123], v[154:157], v[178:181], v[120:123]
	v_mfma_f32_16x16x32_bf16 v[116:119], v[134:137], v[186:189], v[116:119]
	v_mfma_f32_16x16x32_bf16 v[108:111], v[154:157], v[186:189], v[108:111]
	v_mfma_f32_16x16x32_bf16 v[100:103], v[134:137], v[194:197], v[100:103]
	v_mfma_f32_16x16x32_bf16 v[92:95], v[154:157], v[194:197], v[92:95]
	v_mfma_f32_16x16x32_bf16 v[84:87], v[134:137], v[202:205], v[84:87]
	v_mfma_f32_16x16x32_bf16 v[76:79], v[154:157], v[202:205], v[76:79]
	v_mfma_f32_16x16x32_bf16 v[124:127], v[150:153], v[182:185], v[124:127]
	v_mfma_f32_16x16x32_bf16 v[120:123], v[158:161], v[182:185], v[120:123]
	v_mfma_f32_16x16x32_bf16 v[116:119], v[150:153], v[190:193], v[116:119]
	v_mfma_f32_16x16x32_bf16 v[108:111], v[158:161], v[190:193], v[108:111]
	v_mfma_f32_16x16x32_bf16 v[100:103], v[150:153], v[198:201], v[100:103]
	v_mfma_f32_16x16x32_bf16 v[92:95], v[158:161], v[198:201], v[92:95]
	v_mfma_f32_16x16x32_bf16 v[84:87], v[150:153], v[206:209], v[84:87]
	v_mfma_f32_16x16x32_bf16 v[76:79], v[158:161], v[206:209], v[76:79]
	s_setprio 0
	s_barrier
	s_add_i32 s43, 0, 0x14000
	s_add_i32 s38, s38, s18
	v_add_u32_e32 v149, s43, v139
	v_lshl_add_u64 v[162:163], s[8:9], 0, v[166:167]
	s_mov_b32 m0, s38
	ds_read_b128 v[210:213], v149
	ds_read_b128 v[236:239], v149 offset:1024
	ds_read_b128 v[240:243], v149 offset:2048
	ds_read_b128 v[244:247], v149 offset:3072
	global_load_lds_dwordx4 v[162:163], off
	v_lshl_add_u64 v[172:173], s[8:9], 0, v[128:129]
	s_add_i32 m0, s38, 0x2000
	s_nop 0
	global_load_lds_dwordx4 v[172:173], off
	s_barrier
	s_waitcnt lgkmcnt(0)
	s_setprio 1
	s_waitcnt lgkmcnt(0)
	v_mfma_f32_16x16x32_bf16 v[112:115], v[210:213], v[178:181], v[112:115]
	v_mfma_f32_16x16x32_bf16 v[104:107], v[240:243], v[178:181], v[104:107]
	v_mfma_f32_16x16x32_bf16 v[96:99], v[210:213], v[186:189], v[96:99]
	v_mfma_f32_16x16x32_bf16 v[88:91], v[240:243], v[186:189], v[88:91]
	v_mfma_f32_16x16x32_bf16 v[80:83], v[210:213], v[194:197], v[80:83]
	v_mfma_f32_16x16x32_bf16 v[72:75], v[240:243], v[194:197], v[72:75]
	v_mfma_f32_16x16x32_bf16 v[68:71], v[210:213], v[202:205], v[68:71]
	v_mfma_f32_16x16x32_bf16 v[64:67], v[240:243], v[202:205], v[64:67]
	v_mfma_f32_16x16x32_bf16 v[112:115], v[236:239], v[182:185], v[112:115]
	v_mfma_f32_16x16x32_bf16 v[104:107], v[244:247], v[182:185], v[104:107]
	v_mfma_f32_16x16x32_bf16 v[96:99], v[236:239], v[190:193], v[96:99]
	v_mfma_f32_16x16x32_bf16 v[88:91], v[244:247], v[190:193], v[88:91]
	v_mfma_f32_16x16x32_bf16 v[80:83], v[236:239], v[198:201], v[80:83]
	v_mfma_f32_16x16x32_bf16 v[72:75], v[244:247], v[198:201], v[72:75]
	v_mfma_f32_16x16x32_bf16 v[68:71], v[236:239], v[206:209], v[68:71]
	v_mfma_f32_16x16x32_bf16 v[64:67], v[244:247], v[206:209], v[64:67]
	s_setprio 0
	s_mov_b32 m0, s19
	v_lshl_add_u64 v[174:175], s[10:11], 0, v[166:167]
	s_barrier
	ds_read_b128 v[178:181], v148 offset:16384
	ds_read_b128 v[182:185], v148 offset:17408
	ds_read_b128 v[186:189], v148 offset:18432
	ds_read_b128 v[190:193], v148 offset:19456
	ds_read_b128 v[194:197], v148 offset:20480
	ds_read_b128 v[198:201], v148 offset:21504
	ds_read_b128 v[202:205], v148 offset:22528
	ds_read_b128 v[206:209], v148 offset:23552
	global_load_lds_dwordx4 v[174:175], off
	v_lshl_add_u64 v[214:215], s[10:11], 0, v[128:129]
	s_mov_b32 m0, s20
	s_nop 0
	global_load_lds_dwordx4 v[214:215], off
	s_barrier
	s_waitcnt lgkmcnt(0)
	s_setprio 1
	s_waitcnt lgkmcnt(0)
	v_mfma_f32_16x16x32_bf16 v[60:63], v[134:137], v[178:181], v[60:63]
	v_mfma_f32_16x16x32_bf16 v[56:59], v[154:157], v[178:181], v[56:59]
	v_mfma_f32_16x16x32_bf16 v[52:55], v[134:137], v[186:189], v[52:55]
	v_mfma_f32_16x16x32_bf16 v[44:47], v[154:157], v[186:189], v[44:47]
	v_mfma_f32_16x16x32_bf16 v[36:39], v[134:137], v[194:197], v[36:39]
	v_mfma_f32_16x16x32_bf16 v[28:31], v[154:157], v[194:197], v[28:31]
	v_mfma_f32_16x16x32_bf16 v[20:23], v[134:137], v[202:205], v[20:23]
	v_mfma_f32_16x16x32_bf16 v[12:15], v[154:157], v[202:205], v[12:15]
	v_mfma_f32_16x16x32_bf16 v[60:63], v[150:153], v[182:185], v[60:63]
	v_mfma_f32_16x16x32_bf16 v[56:59], v[158:161], v[182:185], v[56:59]
	v_mfma_f32_16x16x32_bf16 v[52:55], v[150:153], v[190:193], v[52:55]
	v_mfma_f32_16x16x32_bf16 v[44:47], v[158:161], v[190:193], v[44:47]
	v_mfma_f32_16x16x32_bf16 v[36:39], v[150:153], v[198:201], v[36:39]
	v_mfma_f32_16x16x32_bf16 v[28:31], v[158:161], v[198:201], v[28:31]
	v_mfma_f32_16x16x32_bf16 v[20:23], v[150:153], v[206:209], v[20:23]
	v_mfma_f32_16x16x32_bf16 v[12:15], v[158:161], v[206:209], v[12:15]
	s_setprio 0
	s_barrier
; #define PG8_STAGE(bufoff, gbase, voff) do { _Pragma("unroll") for (int _i = 0; _i < 2; ++_i) \
;         __builtin_amdgcn_global_load_lds((const unsigned*)((const char*)(gbase) + (voff)[_i]), (PG8_LAS unsigned*)(lds + (bufoff) + ldsw + _i * 8192), 16, 0, 0); } while (0)
; #define PG8_LDA(dst, b, h) do { _Pragma("unroll") for (int m = 0; m < 4; ++m) _Pragma("unroll") for (int k = 0; k < 2; ++k) dst[m][k] = *(const PG8_LAS bf16x8*)(lds + PG8_SA(b, h) + aoff + m * 2048 + k * 1024); } while (0)
; #define PG8_LDB(dst, b, h) do { _Pragma("unroll") for (int n = 0; n < 2; ++n) _Pragma("unroll") for (int k = 0; k < 2; ++k) dst[n][k] = *(const PG8_LAS bf16x8*)(lds + PG8_SB(b, h) + boff + n * 2048 + k * 1024); } while (0)
; #define PG8_MMA(ai, bj, At, Bt) do { __builtin_amdgcn_s_setprio(1); _Pragma("unroll") for (int m = 0; m < 4; ++m) _Pragma("unroll") for (int n = 0; n < 2; ++n) _Pragma("unroll") for (int k = 0; k < 2; ++k) \
;         acc[ai][bj][m][n] = __builtin_amdgcn_mfma_f32_16x16x32_bf16(Bt[n][k], At[m][k], acc[ai][bj][m][n], 0, 0, 0); __builtin_amdgcn_s_setprio(0); } while (0)
; #define PG8_WAIT_V(n) asm volatile("s_waitcnt vmcnt(" #n ")" ::: "memory")
; #define PG8_WAIT_L(n) asm volatile("s_waitcnt lgkmcnt(" #n ")" ::: "memory")
; #define PG8_BAR __builtin_amdgcn_s_barrier()
; #define PG8_SCHED __builtin_amdgcn_sched_barrier(0)
; template <class Epi>
; __device__ __forceinline__ void gemm_phase(PG8_LAS unsigned char* lds, const Gemm g, const Sched& S, const Epi& E) {
;     ...
;             PG8_WAIT_V(6); PG8_BAR; PG8_MMA(1, 1, At, B1); PG8_BAR;
;             PG8_LDB(B0, 1, 0); PG8_SCHED; PG8_LDA(At, 1, 0); PG8_STAGE(PG8_SA(0, 1), a2 + hsA, voffA);
;             PG8_WAIT_L(8); PG8_BAR; PG8_WAIT_L(0); PG8_MMA(0, 0, At, B0); PG8_BAR; PG8_SCHED;
;             PG8_LDB(B1, 1, 1); PG8_STAGE(PG8_SB(1, 0), b3, voffB);
;             PG8_BAR; PG8_WAIT_L(0); PG8_MMA(0, 1, At, B1); PG8_BAR;
;             PG8_LDA(At, 1, 1); PG8_STAGE(PG8_SA(1, 0), a3, voffA);
;             PG8_BAR; PG8_WAIT_L(0); PG8_MMA(1, 0, At, B0); PG8_BAR; PG8_SCHED;
	s_add_u32 s38, s8, 0x40000
	s_addc_u32 s39, s9, 0
	s_add_i32 s43, s43, s18
	v_lshl_add_u64 v[134:135], s[38:39], 0, v[166:167]
	s_mov_b32 m0, s43
	s_nop 0
	global_load_lds_dwordx4 v[134:135], off
	v_lshl_add_u64 v[134:135], s[38:39], 0, v[128:129]
	s_add_i32 m0, s43, 0x2000
	s_nop 0
	global_load_lds_dwordx4 v[134:135], off
	s_waitcnt vmcnt(6)
	s_barrier
	s_setprio 1
	v_mfma_f32_16x16x32_bf16 v[48:51], v[210:213], v[178:181], v[48:51]
	v_mfma_f32_16x16x32_bf16 v[40:43], v[240:243], v[178:181], v[40:43]
	v_mfma_f32_16x16x32_bf16 v[32:35], v[210:213], v[186:189], v[32:35]
	v_mfma_f32_16x16x32_bf16 v[24:27], v[240:243], v[186:189], v[24:27]
	v_mfma_f32_16x16x32_bf16 v[16:19], v[210:213], v[194:197], v[16:19]
	v_mfma_f32_16x16x32_bf16 v[8:11], v[240:243], v[194:197], v[8:11]
	v_mfma_f32_16x16x32_bf16 v[4:7], v[210:213], v[202:205], v[4:7]
	v_mfma_f32_16x16x32_bf16 v[0:3], v[240:243], v[202:205], v[0:3]
	v_mfma_f32_16x16x32_bf16 v[48:51], v[236:239], v[182:185], v[48:51]
	v_mfma_f32_16x16x32_bf16 v[40:43], v[244:247], v[182:185], v[40:43]
	v_mfma_f32_16x16x32_bf16 v[32:35], v[236:239], v[190:193], v[32:35]
	v_mfma_f32_16x16x32_bf16 v[24:27], v[244:247], v[190:193], v[24:27]
	v_mfma_f32_16x16x32_bf16 v[16:19], v[236:239], v[198:201], v[16:19]
	v_mfma_f32_16x16x32_bf16 v[8:11], v[244:247], v[198:201], v[8:11]
	v_mfma_f32_16x16x32_bf16 v[4:7], v[236:239], v[206:209], v[4:7]
	v_mfma_f32_16x16x32_bf16 v[0:3], v[244:247], v[206:209], v[0:3]
	s_setprio 0
	s_add_i32 s38, 0, 0x18000
	v_add_u32_e32 v149, s38, v139
	s_barrier
	ds_read_b128 v[134:137], v149
	ds_read_b128 v[150:153], v149 offset:1024
	ds_read_b128 v[154:157], v149 offset:2048
	ds_read_b128 v[158:161], v149 offset:3072
	s_add_u32 s10, s10, 0x40000
	s_addc_u32 s11, s11, 0
	s_mov_b32 m0, s21
	v_lshl_add_u64 v[210:211], s[10:11], 0, v[166:167]
	ds_read_b128 v[178:181], v148 offset:32768
	ds_read_b128 v[182:185], v148 offset:33792
	ds_read_b128 v[186:189], v148 offset:34816
	ds_read_b128 v[190:193], v148 offset:35840
	ds_read_b128 v[194:197], v148 offset:36864
	ds_read_b128 v[198:201], v148 offset:37888
	ds_read_b128 v[202:205], v148 offset:38912
	ds_read_b128 v[206:209], v148 offset:39936
	global_load_lds_dwordx4 v[210:211], off
	v_lshl_add_u64 v[210:211], s[10:11], 0, v[128:129]
	s_mov_b32 m0, s22
	s_nop 0
	global_load_lds_dwordx4 v[210:211], off
	s_waitcnt lgkmcnt(8)
	s_barrier
	s_waitcnt lgkmcnt(0)
	s_setprio 1
	s_waitcnt lgkmcnt(0)
	v_mfma_f32_16x16x32_bf16 v[124:127], v[134:137], v[178:181], v[124:127]
	v_mfma_f32_16x16x32_bf16 v[120:123], v[154:157], v[178:181], v[120:123]
	v_mfma_f32_16x16x32_bf16 v[116:119], v[134:137], v[186:189], v[116:119]
	v_mfma_f32_16x16x32_bf16 v[108:111], v[154:157], v[186:189], v[108:111]
	v_mfma_f32_16x16x32_bf16 v[100:103], v[134:137], v[194:197], v[100:103]
	v_mfma_f32_16x16x32_bf16 v[92:95], v[154:157], v[194:197], v[92:95]
	v_mfma_f32_16x16x32_bf16 v[84:87], v[134:137], v[202:205], v[84:87]
	v_mfma_f32_16x16x32_bf16 v[76:79], v[154:157], v[202:205], v[76:79]
	v_mfma_f32_16x16x32_bf16 v[124:127], v[150:153], v[182:185], v[124:127]
	v_mfma_f32_16x16x32_bf16 v[120:123], v[158:161], v[182:185], v[120:123]
	v_mfma_f32_16x16x32_bf16 v[116:119], v[150:153], v[190:193], v[116:119]
	v_mfma_f32_16x16x32_bf16 v[108:111], v[158:161], v[190:193], v[108:111]
	v_mfma_f32_16x16x32_bf16 v[100:103], v[150:153], v[198:201], v[100:103]
	v_mfma_f32_16x16x32_bf16 v[92:95], v[158:161], v[198:201], v[92:95]
	v_mfma_f32_16x16x32_bf16 v[84:87], v[150:153], v[206:209], v[84:87]
	v_mfma_f32_16x16x32_bf16 v[76:79], v[158:161], v[206:209], v[76:79]
	s_setprio 0
	s_barrier
	s_add_i32 s10, 0, 0x1c000
	s_add_i32 s11, s38, s18
	v_add_u32_e32 v149, s10, v139
	v_lshl_add_u64 v[162:163], v[162:163], 0, s[76:77]
	s_mov_b32 m0, s11
	ds_read_b128 v[210:213], v149
	ds_read_b128 v[236:239], v149 offset:1024
	ds_read_b128 v[240:243], v149 offset:2048
	ds_read_b128 v[244:247], v149 offset:3072
	global_load_lds_dwordx4 v[162:163], off
	v_lshl_add_u64 v[162:163], v[172:173], 0, s[76:77]
	s_add_i32 m0, s11, 0x2000
	s_nop 0
	global_load_lds_dwordx4 v[162:163], off
	s_barrier
	s_waitcnt lgkmcnt(0)
	s_setprio 1
	s_waitcnt lgkmcnt(0)
	v_mfma_f32_16x16x32_bf16 v[112:115], v[210:213], v[178:181], v[112:115]
	v_mfma_f32_16x16x32_bf16 v[104:107], v[240:243], v[178:181], v[104:107]
	v_mfma_f32_16x16x32_bf16 v[96:99], v[210:213], v[186:189], v[96:99]
	v_mfma_f32_16x16x32_bf16 v[88:91], v[240:243], v[186:189], v[88:91]
	v_mfma_f32_16x16x32_bf16 v[80:83], v[210:213], v[194:197], v[80:83]
	v_mfma_f32_16x16x32_bf16 v[72:75], v[240:243], v[194:197], v[72:75]
	v_mfma_f32_16x16x32_bf16 v[68:71], v[210:213], v[202:205], v[68:71]
	v_mfma_f32_16x16x32_bf16 v[64:67], v[240:243], v[202:205], v[64:67]
	v_mfma_f32_16x16x32_bf16 v[112:115], v[236:239], v[182:185], v[112:115]
	v_mfma_f32_16x16x32_bf16 v[104:107], v[244:247], v[182:185], v[104:107]
	v_mfma_f32_16x16x32_bf16 v[96:99], v[236:239], v[190:193], v[96:99]
	v_mfma_f32_16x16x32_bf16 v[88:91], v[244:247], v[190:193], v[88:91]
	v_mfma_f32_16x16x32_bf16 v[80:83], v[236:239], v[198:201], v[80:83]
	v_mfma_f32_16x16x32_bf16 v[72:75], v[244:247], v[198:201], v[72:75]
	v_mfma_f32_16x16x32_bf16 v[68:71], v[236:239], v[206:209], v[68:71]
	v_mfma_f32_16x16x32_bf16 v[64:67], v[244:247], v[206:209], v[64:67]
	s_setprio 0
	s_mov_b32 m0, s24
	v_lshl_add_u64 v[162:163], v[174:175], 0, s[76:77]
	s_barrier
	ds_read_b128 v[178:181], v148 offset:49152
	ds_read_b128 v[182:185], v148 offset:50176
	ds_read_b128 v[186:189], v148 offset:51200
	ds_read_b128 v[190:193], v148 offset:52224
	ds_read_b128 v[194:197], v148 offset:53248
	ds_read_b128 v[198:201], v148 offset:54272
	ds_read_b128 v[202:205], v148 offset:55296
	ds_read_b128 v[206:209], v148 offset:56320
	global_load_lds_dwordx4 v[162:163], off
	v_lshl_add_u64 v[162:163], v[214:215], 0, s[76:77]
	s_mov_b32 m0, s25
	s_nop 0
	global_load_lds_dwordx4 v[162:163], off
	s_barrier
; __device__ __forceinline__ uint32_t pack2(float a, float b) { uint32_t r; asm("v_cvt_pk_bf16_f32 %0, %1, %2" : "=v"(r) : "v"(a), "v"(b)); return r; }
; #define PG8_STAGE(bufoff, gbase, voff) do { _Pragma("unroll") for (int _i = 0; _i < 2; ++_i) \
;         __builtin_amdgcn_global_load_lds((const unsigned*)((const char*)(gbase) + (voff)[_i]), (PG8_LAS unsigned*)(lds + (bufoff) + ldsw + _i * 8192), 16, 0, 0); } while (0)
; #define PG8_MMA(ai, bj, At, Bt) do { __builtin_amdgcn_s_setprio(1); _Pragma("unroll") for (int m = 0; m < 4; ++m) _Pragma("unroll") for (int n = 0; n < 2; ++n) _Pragma("unroll") for (int k = 0; k < 2; ++k) \
;         acc[ai][bj][m][n] = __builtin_amdgcn_mfma_f32_16x16x32_bf16(Bt[n][k], At[m][k], acc[ai][bj][m][n], 0, 0, 0); __builtin_amdgcn_s_setprio(0); } while (0)
; #define PG8_WAIT_V(n) asm volatile("s_waitcnt vmcnt(" #n ")" ::: "memory")
; #define PG8_WAIT_L(n) asm volatile("s_waitcnt lgkmcnt(" #n ")" ::: "memory")
; #define PG8_BAR __builtin_amdgcn_s_barrier()
; #define PG8_SCHED __builtin_amdgcn_sched_barrier(0)
; template <class Epi>
; __device__ __forceinline__ void gemm_phase(PG8_LAS unsigned char* lds, const Gemm g, const Sched& S, const Epi& E) {
;     ...
;             PG8_BAR; PG8_WAIT_L(0); PG8_MMA(1, 0, At, B0); PG8_BAR; PG8_SCHED;
;             PG8_STAGE(PG8_SB(1, 1), b3 + hsB, voffB);
;             PG8_WAIT_V(6); PG8_BAR; PG8_MMA(1, 1, At, B1); PG8_BAR;
;         }
;         E(acc, cur, wr, wc, fr, fq);
;   __device__ __forceinline__ void operator()(const f32x4 (&acc)[2][2][4][2], const pg8::Unit& u, int wr, int wc, int fr, int fq) const {
;     ...
;         } else if (kind == EPI_E1) {
; #pragma unroll
;           for (int bj = 0; bj < 2; ++bj)
; #pragma unroll
;             for (int n = 0; n < 2; ++n) {
;               int cc = u.pn * 256 + bj * 128 + wc * 32 + n * 16 + fq * 4;
;               float sc = (cc >= 1184 && cc < 1696) ? 0.08838834764831845f : 1.0f;
;               f32x4 a = acc[ai][bj][m][n];
;               uint2 o; o.x = pack2(a[0] * sc, a[1] * sc); o.y = pack2(a[2] * sc, a[3] * sc);
;               *(uint2*)(outb + (size_t)row * PW + cc) = o;
;               if (cc >= 2720 && cc < 2736) *(float4*)(outf + (size_t)row * 16 + (cc - 2720)) = make_float4(a[0], a[1], a[2], a[3]);
;             }
	s_waitcnt lgkmcnt(0)
	s_setprio 1
	s_waitcnt lgkmcnt(0)
	v_mfma_f32_16x16x32_bf16 v[60:63], v[134:137], v[178:181], v[60:63]
	v_mfma_f32_16x16x32_bf16 v[56:59], v[154:157], v[178:181], v[56:59]
	v_mfma_f32_16x16x32_bf16 v[52:55], v[134:137], v[186:189], v[52:55]
	v_mfma_f32_16x16x32_bf16 v[44:47], v[154:157], v[186:189], v[44:47]
	v_mfma_f32_16x16x32_bf16 v[36:39], v[134:137], v[194:197], v[36:39]
	v_mfma_f32_16x16x32_bf16 v[28:31], v[154:157], v[194:197], v[28:31]
	v_mfma_f32_16x16x32_bf16 v[20:23], v[134:137], v[202:205], v[20:23]
	v_mfma_f32_16x16x32_bf16 v[12:15], v[154:157], v[202:205], v[12:15]
	v_mfma_f32_16x16x32_bf16 v[60:63], v[150:153], v[182:185], v[60:63]
	v_mfma_f32_16x16x32_bf16 v[56:59], v[158:161], v[182:185], v[56:59]
	v_mfma_f32_16x16x32_bf16 v[52:55], v[150:153], v[190:193], v[52:55]
	v_mfma_f32_16x16x32_bf16 v[44:47], v[158:161], v[190:193], v[44:47]
	v_mfma_f32_16x16x32_bf16 v[36:39], v[150:153], v[198:201], v[36:39]
	v_mfma_f32_16x16x32_bf16 v[28:31], v[158:161], v[198:201], v[28:31]
	v_mfma_f32_16x16x32_bf16 v[20:23], v[150:153], v[206:209], v[20:23]
	v_mfma_f32_16x16x32_bf16 v[12:15], v[158:161], v[206:209], v[12:15]
	s_setprio 0
	s_barrier
	s_add_u32 s8, s8, 0x40080
	s_addc_u32 s9, s9, 0
	s_add_i32 s10, s10, s18
	v_lshl_add_u64 v[134:135], s[8:9], 0, v[166:167]
	s_mov_b32 m0, s10
	s_nop 0
	global_load_lds_dwordx4 v[134:135], off
	v_lshl_add_u64 v[134:135], s[8:9], 0, v[128:129]
	s_add_i32 m0, s10, 0x2000
	s_nop 0
	global_load_lds_dwordx4 v[134:135], off
	s_waitcnt vmcnt(6)
	s_barrier
	s_setprio 1
	v_mfma_f32_16x16x32_bf16 v[48:51], v[210:213], v[178:181], v[48:51]
	v_mfma_f32_16x16x32_bf16 v[40:43], v[240:243], v[178:181], v[40:43]
	v_mfma_f32_16x16x32_bf16 v[32:35], v[210:213], v[186:189], v[32:35]
	v_mfma_f32_16x16x32_bf16 v[24:27], v[240:243], v[186:189], v[24:27]
	v_mfma_f32_16x16x32_bf16 v[16:19], v[210:213], v[194:197], v[16:19]
	v_mfma_f32_16x16x32_bf16 v[8:11], v[240:243], v[194:197], v[8:11]
	v_mfma_f32_16x16x32_bf16 v[4:7], v[210:213], v[202:205], v[4:7]
	v_mfma_f32_16x16x32_bf16 v[0:3], v[240:243], v[202:205], v[0:3]
	v_mfma_f32_16x16x32_bf16 v[48:51], v[236:239], v[182:185], v[48:51]
	v_mfma_f32_16x16x32_bf16 v[40:43], v[244:247], v[182:185], v[40:43]
	v_mfma_f32_16x16x32_bf16 v[32:35], v[236:239], v[190:193], v[32:35]
	v_mfma_f32_16x16x32_bf16 v[24:27], v[244:247], v[190:193], v[24:27]
	v_mfma_f32_16x16x32_bf16 v[16:19], v[236:239], v[198:201], v[16:19]
	v_mfma_f32_16x16x32_bf16 v[8:11], v[244:247], v[198:201], v[8:11]
	v_mfma_f32_16x16x32_bf16 v[4:7], v[236:239], v[206:209], v[4:7]
	v_mfma_f32_16x16x32_bf16 v[0:3], v[244:247], v[206:209], v[0:3]
	s_setprio 0
	s_add_i32 s37, s37, 2
	s_add_u32 s6, s6, 0x100
	s_addc_u32 s7, s7, 0
	s_add_u32 s30, s30, 0x100
	s_addc_u32 s36, s36, 0
	s_cmp_gt_u32 s37, 13
	s_barrier
	s_cbranch_scc0 .LBB0_799
	s_lshl_b32 s3, s42, 8
	s_or_b32 s3, s3, s23
	s_lshl_b32 s2, s4, 8
	s_add_i32 s4, s3, 0xfffffb60
	s_cmpk_lt_u32 s4, 0x200
	s_cselect_b64 vcc, -1, 0
	v_cndmask_b32_e32 v204, 1.0, v232, vcc
	s_add_i32 s4, s3, 0xfffffb70
	s_cmpk_lt_u32 s4, 0x200
	s_cselect_b64 vcc, -1, 0
	v_cndmask_b32_e32 v205, 1.0, v232, vcc
	s_add_i32 s4, s3, 0xfffffbe0
	s_cmpk_lt_u32 s4, 0x200
	s_cselect_b64 vcc, -1, 0
	v_cndmask_b32_e32 v206, 1.0, v232, vcc
	s_add_i32 s4, s3, 0xfffffbf0
	s_cmpk_lt_u32 s4, 0x200
	s_cselect_b64 vcc, -1, 0
	v_cndmask_b32_e32 v207, 1.0, v232, vcc
	v_and_b32_e32 v158, 16, v231
	v_lshrrev_b32_e32 v159, 1, v158
	v_add_u32_e32 v158, v158, v159
	v_or_b32_e32 v159, s3, v140
	v_lshl_add_u32 v194, v159, 1, v158
	v_mov_b32_e32 v195, 0
	v_add_u32_e32 v178, s2, v138
	v_mul_u32_u24_e32 v178, 0x1600, v178
	v_mov_b32_e32 v179, 0
	v_lshl_add_u64 v[178:179], s[44:45], 0, v[178:179]
	v_lshl_add_u64 v[178:179], v[178:179], 0, v[194:195]
	v_add_u32_e32 v180, s2, v141
	v_mul_u32_u24_e32 v180, 0x1600, v180
	v_mov_b32_e32 v181, 0
	v_lshl_add_u64 v[180:181], s[44:45], 0, v[180:181]
	v_lshl_add_u64 v[180:181], v[180:181], 0, v[194:195]
	v_add_u32_e32 v182, s2, v142
	v_mul_u32_u24_e32 v182, 0x1600, v182
	v_mov_b32_e32 v183, 0
	v_lshl_add_u64 v[182:183], s[44:45], 0, v[182:183]
	v_lshl_add_u64 v[182:183], v[182:183], 0, v[194:195]
	v_add_u32_e32 v184, s2, v143
	v_mul_u32_u24_e32 v184, 0x1600, v184
	v_mov_b32_e32 v185, 0
	v_lshl_add_u64 v[184:185], s[44:45], 0, v[184:185]
	v_lshl_add_u64 v[184:185], v[184:185], 0, v[194:195]
	v_add_u32_e32 v186, s2, v144
	v_mul_u32_u24_e32 v186, 0x1600, v186
	v_mov_b32_e32 v187, 0
	v_lshl_add_u64 v[186:187], s[44:45], 0, v[186:187]
	v_lshl_add_u64 v[186:187], v[186:187], 0, v[194:195]
	v_add_u32_e32 v188, s2, v145
	v_mul_u32_u24_e32 v188, 0x1600, v188
	v_mov_b32_e32 v189, 0
	v_lshl_add_u64 v[188:189], s[44:45], 0, v[188:189]
	v_lshl_add_u64 v[188:189], v[188:189], 0, v[194:195]
	v_add_u32_e32 v190, s2, v146
	v_mul_u32_u24_e32 v190, 0x1600, v190
	v_mov_b32_e32 v191, 0
	v_lshl_add_u64 v[190:191], s[44:45], 0, v[190:191]
	v_lshl_add_u64 v[190:191], v[190:191], 0, v[194:195]
	v_add_u32_e32 v192, s2, v147
	v_mul_u32_u24_e32 v192, 0x1600, v192
	v_mov_b32_e32 v193, 0
	v_lshl_add_u64 v[192:193], s[44:45], 0, v[192:193]
	v_lshl_add_u64 v[192:193], v[192:193], 0, v[194:195]
	v_mul_f32_e32 v196, v204, v124
	v_mul_f32_e32 v197, v204, v125
	v_cvt_pk_bf16_f32 v196, v196, v197
	v_mul_f32_e32 v197, v204, v126
	v_mul_f32_e32 v208, v204, v127
	v_cvt_pk_bf16_f32 v197, v197, v208
	v_mul_f32_e32 v198, v205, v120
	v_mul_f32_e32 v199, v205, v121
	v_cvt_pk_bf16_f32 v198, v198, v199
	v_mul_f32_e32 v199, v205, v122
	v_mul_f32_e32 v208, v205, v123
	v_cvt_pk_bf16_f32 v199, v199, v208
	s_nop 1
	v_permlane16_swap_b32_e32 v196, v198
	v_permlane16_swap_b32_e32 v197, v199
; __device__ __forceinline__ uint32_t pack2(float a, float b) { uint32_t r; asm("v_cvt_pk_bf16_f32 %0, %1, %2" : "=v"(r) : "v"(a), "v"(b)); return r; }
;   __device__ __forceinline__ void operator()(const f32x4 (&acc)[2][2][4][2], const pg8::Unit& u, int wr, int wc, int fr, int fq) const {
;     ...
;         } else if (kind == EPI_E1) {
; #pragma unroll
;           for (int bj = 0; bj < 2; ++bj)
; #pragma unroll
;             for (int n = 0; n < 2; ++n) {
;               int cc = u.pn * 256 + bj * 128 + wc * 32 + n * 16 + fq * 4;
;               float sc = (cc >= 1184 && cc < 1696) ? 0.08838834764831845f : 1.0f;
;               f32x4 a = acc[ai][bj][m][n];
;               uint2 o; o.x = pack2(a[0] * sc, a[1] * sc); o.y = pack2(a[2] * sc, a[3] * sc);
;               *(uint2*)(outb + (size_t)row * PW + cc) = o;
;               if (cc >= 2720 && cc < 2736) *(float4*)(outf + (size_t)row * 16 + (cc - 2720)) = make_float4(a[0], a[1], a[2], a[3]);
;             }
	global_store_dwordx4 v[178:179], v[196:199], off
	v_mul_f32_e32 v200, v206, v112
	v_mul_f32_e32 v201, v206, v113
	v_cvt_pk_bf16_f32 v200, v200, v201
	v_mul_f32_e32 v201, v206, v114
	v_mul_f32_e32 v208, v206, v115
	v_cvt_pk_bf16_f32 v201, v201, v208
	v_mul_f32_e32 v202, v207, v104
	v_mul_f32_e32 v203, v207, v105
	v_cvt_pk_bf16_f32 v202, v202, v203
	v_mul_f32_e32 v203, v207, v106
	v_mul_f32_e32 v208, v207, v107
	v_cvt_pk_bf16_f32 v203, v203, v208
	s_nop 1
	v_permlane16_swap_b32_e32 v200, v202
	v_permlane16_swap_b32_e32 v201, v203
	global_store_dwordx4 v[178:179], v[200:203], off offset:256
	v_mul_f32_e32 v150, v204, v116
	v_mul_f32_e32 v151, v204, v117
	v_cvt_pk_bf16_f32 v150, v150, v151
	v_mul_f32_e32 v151, v204, v118
	v_mul_f32_e32 v208, v204, v119
	v_cvt_pk_bf16_f32 v151, v151, v208
	v_mul_f32_e32 v152, v205, v108
	v_mul_f32_e32 v153, v205, v109
	v_cvt_pk_bf16_f32 v152, v152, v153
	v_mul_f32_e32 v153, v205, v110
	v_mul_f32_e32 v208, v205, v111
	v_cvt_pk_bf16_f32 v153, v153, v208
	s_nop 1
	v_permlane16_swap_b32_e32 v150, v152
	v_permlane16_swap_b32_e32 v151, v153
	global_store_dwordx4 v[180:181], v[150:153], off
	v_mul_f32_e32 v154, v206, v96
	v_mul_f32_e32 v155, v206, v97
	v_cvt_pk_bf16_f32 v154, v154, v155
	v_mul_f32_e32 v155, v206, v98
	v_mul_f32_e32 v208, v206, v99
	v_cvt_pk_bf16_f32 v155, v155, v208
	v_mul_f32_e32 v156, v207, v88
	v_mul_f32_e32 v157, v207, v89
	v_cvt_pk_bf16_f32 v156, v156, v157
	v_mul_f32_e32 v157, v207, v90
	v_mul_f32_e32 v208, v207, v91
	v_cvt_pk_bf16_f32 v157, v157, v208
	s_nop 1
	v_permlane16_swap_b32_e32 v154, v156
	v_permlane16_swap_b32_e32 v155, v157
	global_store_dwordx4 v[180:181], v[154:157], off offset:256
	v_mul_f32_e32 v196, v204, v100
	v_mul_f32_e32 v197, v204, v101
	v_cvt_pk_bf16_f32 v196, v196, v197
	v_mul_f32_e32 v197, v204, v102
	v_mul_f32_e32 v208, v204, v103
	v_cvt_pk_bf16_f32 v197, v197, v208
	v_mul_f32_e32 v198, v205, v92
	v_mul_f32_e32 v199, v205, v93
	v_cvt_pk_bf16_f32 v198, v198, v199
	v_mul_f32_e32 v199, v205, v94
	v_mul_f32_e32 v208, v205, v95
	v_cvt_pk_bf16_f32 v199, v199, v208
	s_nop 1
	v_permlane16_swap_b32_e32 v196, v198
	v_permlane16_swap_b32_e32 v197, v199
	global_store_dwordx4 v[182:183], v[196:199], off
	v_mul_f32_e32 v200, v206, v80
	v_mul_f32_e32 v201, v206, v81
	v_cvt_pk_bf16_f32 v200, v200, v201
	v_mul_f32_e32 v201, v206, v82
	v_mul_f32_e32 v208, v206, v83
	v_cvt_pk_bf16_f32 v201, v201, v208
	v_mul_f32_e32 v202, v207, v72
	v_mul_f32_e32 v203, v207, v73
	v_cvt_pk_bf16_f32 v202, v202, v203
	v_mul_f32_e32 v203, v207, v74
	v_mul_f32_e32 v208, v207, v75
	v_cvt_pk_bf16_f32 v203, v203, v208
	s_nop 1
	v_permlane16_swap_b32_e32 v200, v202
	v_permlane16_swap_b32_e32 v201, v203
	global_store_dwordx4 v[182:183], v[200:203], off offset:256
	v_mul_f32_e32 v150, v204, v84
	v_mul_f32_e32 v151, v204, v85
	v_cvt_pk_bf16_f32 v150, v150, v151
	v_mul_f32_e32 v151, v204, v86
	v_mul_f32_e32 v208, v204, v87
	v_cvt_pk_bf16_f32 v151, v151, v208
	v_mul_f32_e32 v152, v205, v76
	v_mul_f32_e32 v153, v205, v77
	v_cvt_pk_bf16_f32 v152, v152, v153
	v_mul_f32_e32 v153, v205, v78
	v_mul_f32_e32 v208, v205, v79
	v_cvt_pk_bf16_f32 v153, v153, v208
	s_nop 1
	v_permlane16_swap_b32_e32 v150, v152
	v_permlane16_swap_b32_e32 v151, v153
	global_store_dwordx4 v[184:185], v[150:153], off
	v_mul_f32_e32 v154, v206, v68
	v_mul_f32_e32 v155, v206, v69
	v_cvt_pk_bf16_f32 v154, v154, v155
	v_mul_f32_e32 v155, v206, v70
	v_mul_f32_e32 v208, v206, v71
	v_cvt_pk_bf16_f32 v155, v155, v208
	v_mul_f32_e32 v156, v207, v64
	v_mul_f32_e32 v157, v207, v65
	v_cvt_pk_bf16_f32 v156, v156, v157
	v_mul_f32_e32 v157, v207, v66
	v_mul_f32_e32 v208, v207, v67
	v_cvt_pk_bf16_f32 v157, v157, v208
	s_nop 1
	v_permlane16_swap_b32_e32 v154, v156
	v_permlane16_swap_b32_e32 v155, v157
	global_store_dwordx4 v[184:185], v[154:157], off offset:256
	v_mul_f32_e32 v196, v204, v60
	v_mul_f32_e32 v197, v204, v61
	v_cvt_pk_bf16_f32 v196, v196, v197
	v_mul_f32_e32 v197, v204, v62
	v_mul_f32_e32 v208, v204, v63
	v_cvt_pk_bf16_f32 v197, v197, v208
	v_mul_f32_e32 v198, v205, v56
	v_mul_f32_e32 v199, v205, v57
	v_cvt_pk_bf16_f32 v198, v198, v199
	v_mul_f32_e32 v199, v205, v58
	v_mul_f32_e32 v208, v205, v59
	v_cvt_pk_bf16_f32 v199, v199, v208
	s_nop 1
	v_permlane16_swap_b32_e32 v196, v198
	v_permlane16_swap_b32_e32 v197, v199
	global_store_dwordx4 v[186:187], v[196:199], off
	v_mul_f32_e32 v200, v206, v48
	v_mul_f32_e32 v201, v206, v49
	v_cvt_pk_bf16_f32 v200, v200, v201
	v_mul_f32_e32 v201, v206, v50
	v_mul_f32_e32 v208, v206, v51
	v_cvt_pk_bf16_f32 v201, v201, v208
	v_mul_f32_e32 v202, v207, v40
	v_mul_f32_e32 v203, v207, v41
	v_cvt_pk_bf16_f32 v202, v202, v203
	v_mul_f32_e32 v203, v207, v42
	v_mul_f32_e32 v208, v207, v43
	v_cvt_pk_bf16_f32 v203, v203, v208
	s_nop 1
	v_permlane16_swap_b32_e32 v200, v202
	v_permlane16_swap_b32_e32 v201, v203
	global_store_dwordx4 v[186:187], v[200:203], off offset:256
	v_mul_f32_e32 v150, v204, v52
	v_mul_f32_e32 v151, v204, v53
	v_cvt_pk_bf16_f32 v150, v150, v151
	v_mul_f32_e32 v151, v204, v54
	v_mul_f32_e32 v208, v204, v55
	v_cvt_pk_bf16_f32 v151, v151, v208
	v_mul_f32_e32 v152, v205, v44
	v_mul_f32_e32 v153, v205, v45
	v_cvt_pk_bf16_f32 v152, v152, v153
; __device__ __forceinline__ uint32_t pack2(float a, float b) { uint32_t r; asm("v_cvt_pk_bf16_f32 %0, %1, %2" : "=v"(r) : "v"(a), "v"(b)); return r; }
; template <class Epi>
; __device__ __forceinline__ void gemm_phase(PG8_LAS unsigned char* lds, const Gemm g, const Sched& S, const Epi& E) {
;     ...
;         E(acc, cur, wr, wc, fr, fq);
;         if (!has_next) break;
; #pragma unroll
;         for (int a = 0; a < 2; ++a)
; #pragma unroll
;             for (int b = 0; b < 2; ++b)
; #pragma unroll
;                 for (int m = 0; m < 4; ++m)
; #pragma unroll
;                     for (int n = 0; n < 2; ++n) acc[a][b][m][n] = (f32x4){0.f, 0.f, 0.f, 0.f};
;         cur = nxt; cA = nA; cB = nB; ++ui;
;   __device__ __forceinline__ void operator()(const f32x4 (&acc)[2][2][4][2], const pg8::Unit& u, int wr, int wc, int fr, int fq) const {
;     ...
;         } else if (kind == EPI_E1) {
; #pragma unroll
;           for (int bj = 0; bj < 2; ++bj)
; #pragma unroll
;             for (int n = 0; n < 2; ++n) {
;               int cc = u.pn * 256 + bj * 128 + wc * 32 + n * 16 + fq * 4;
;               float sc = (cc >= 1184 && cc < 1696) ? 0.08838834764831845f : 1.0f;
;               f32x4 a = acc[ai][bj][m][n];
;               uint2 o; o.x = pack2(a[0] * sc, a[1] * sc); o.y = pack2(a[2] * sc, a[3] * sc);
;               *(uint2*)(outb + (size_t)row * PW + cc) = o;
;               if (cc >= 2720 && cc < 2736) *(float4*)(outf + (size_t)row * 16 + (cc - 2720)) = make_float4(a[0], a[1], a[2], a[3]);
;             }
	v_mul_f32_e32 v153, v205, v46
	v_mul_f32_e32 v208, v205, v47
	v_cvt_pk_bf16_f32 v153, v153, v208
	s_nop 1
	v_permlane16_swap_b32_e32 v150, v152
	v_permlane16_swap_b32_e32 v151, v153
	global_store_dwordx4 v[188:189], v[150:153], off
	v_mul_f32_e32 v154, v206, v32
	v_mul_f32_e32 v155, v206, v33
	v_cvt_pk_bf16_f32 v154, v154, v155
	v_mul_f32_e32 v155, v206, v34
	v_mul_f32_e32 v208, v206, v35
	v_cvt_pk_bf16_f32 v155, v155, v208
	v_mul_f32_e32 v156, v207, v24
	v_mul_f32_e32 v157, v207, v25
	v_cvt_pk_bf16_f32 v156, v156, v157
	v_mul_f32_e32 v157, v207, v26
	v_mul_f32_e32 v208, v207, v27
	v_cvt_pk_bf16_f32 v157, v157, v208
	s_nop 1
	v_permlane16_swap_b32_e32 v154, v156
	v_permlane16_swap_b32_e32 v155, v157
	global_store_dwordx4 v[188:189], v[154:157], off offset:256
	v_mul_f32_e32 v196, v204, v36
	v_mul_f32_e32 v197, v204, v37
	v_cvt_pk_bf16_f32 v196, v196, v197
	v_mul_f32_e32 v197, v204, v38
	v_mul_f32_e32 v208, v204, v39
	v_cvt_pk_bf16_f32 v197, v197, v208
	v_mul_f32_e32 v198, v205, v28
	v_mul_f32_e32 v199, v205, v29
	v_cvt_pk_bf16_f32 v198, v198, v199
	v_mul_f32_e32 v199, v205, v30
	v_mul_f32_e32 v208, v205, v31
	v_cvt_pk_bf16_f32 v199, v199, v208
	s_nop 1
	v_permlane16_swap_b32_e32 v196, v198
	v_permlane16_swap_b32_e32 v197, v199
	global_store_dwordx4 v[190:191], v[196:199], off
	v_mul_f32_e32 v200, v206, v16
	v_mul_f32_e32 v201, v206, v17
	v_cvt_pk_bf16_f32 v200, v200, v201
	v_mul_f32_e32 v201, v206, v18
	v_mul_f32_e32 v208, v206, v19
	v_cvt_pk_bf16_f32 v201, v201, v208
	v_mul_f32_e32 v202, v207, v8
	v_mul_f32_e32 v203, v207, v9
	v_cvt_pk_bf16_f32 v202, v202, v203
	v_mul_f32_e32 v203, v207, v10
	v_mul_f32_e32 v208, v207, v11
	v_cvt_pk_bf16_f32 v203, v203, v208
	s_nop 1
	v_permlane16_swap_b32_e32 v200, v202
	v_permlane16_swap_b32_e32 v201, v203
	global_store_dwordx4 v[190:191], v[200:203], off offset:256
	v_mul_f32_e32 v150, v204, v20
	v_mul_f32_e32 v151, v204, v21
	v_cvt_pk_bf16_f32 v150, v150, v151
	v_mul_f32_e32 v151, v204, v22
	v_mul_f32_e32 v208, v204, v23
	v_cvt_pk_bf16_f32 v151, v151, v208
	v_mul_f32_e32 v152, v205, v12
	v_mul_f32_e32 v153, v205, v13
	v_cvt_pk_bf16_f32 v152, v152, v153
	v_mul_f32_e32 v153, v205, v14
	v_mul_f32_e32 v208, v205, v15
	v_cvt_pk_bf16_f32 v153, v153, v208
	s_nop 1
	v_permlane16_swap_b32_e32 v150, v152
	v_permlane16_swap_b32_e32 v151, v153
	global_store_dwordx4 v[192:193], v[150:153], off
	v_mul_f32_e32 v154, v206, v4
	v_mul_f32_e32 v155, v206, v5
	v_cvt_pk_bf16_f32 v154, v154, v155
	v_mul_f32_e32 v155, v206, v6
	v_mul_f32_e32 v208, v206, v7
	v_cvt_pk_bf16_f32 v155, v155, v208
	v_mul_f32_e32 v156, v207, v0
	v_mul_f32_e32 v157, v207, v1
	v_cvt_pk_bf16_f32 v156, v156, v157
	v_mul_f32_e32 v157, v207, v2
	v_mul_f32_e32 v208, v207, v3
	v_cvt_pk_bf16_f32 v157, v157, v208
	s_nop 1
	v_permlane16_swap_b32_e32 v154, v156
	v_permlane16_swap_b32_e32 v155, v157
	global_store_dwordx4 v[192:193], v[154:157], off offset:256
	s_cmpk_lg_i32 s3, 0xa20
	s_cbranch_scc1 .Le1_nogate
	v_lshlrev_b32_e32 v158, 2, v140
	v_mov_b32_e32 v159, 0
	v_add_u32_e32 v196, s2, v138
	v_mov_b32_e32 v197, 0
	v_lshlrev_b64 v[196:197], 6, v[196:197]
	v_lshl_add_u64 v[196:197], s[46:47], 0, v[196:197]
	v_lshl_add_u64 v[196:197], v[196:197], 0, v[158:159]
	global_store_dwordx4 v[196:197], v[112:115], off
	v_add_u32_e32 v196, s2, v141
	v_mov_b32_e32 v197, 0
	v_lshlrev_b64 v[196:197], 6, v[196:197]
	v_lshl_add_u64 v[196:197], s[46:47], 0, v[196:197]
	v_lshl_add_u64 v[196:197], v[196:197], 0, v[158:159]
	global_store_dwordx4 v[196:197], v[96:99], off
	v_add_u32_e32 v196, s2, v142
	v_mov_b32_e32 v197, 0
	v_lshlrev_b64 v[196:197], 6, v[196:197]
	v_lshl_add_u64 v[196:197], s[46:47], 0, v[196:197]
	v_lshl_add_u64 v[196:197], v[196:197], 0, v[158:159]
	global_store_dwordx4 v[196:197], v[80:83], off
	v_add_u32_e32 v196, s2, v143
	v_mov_b32_e32 v197, 0
	v_lshlrev_b64 v[196:197], 6, v[196:197]
	v_lshl_add_u64 v[196:197], s[46:47], 0, v[196:197]
	v_lshl_add_u64 v[196:197], v[196:197], 0, v[158:159]
	global_store_dwordx4 v[196:197], v[68:71], off
	v_add_u32_e32 v196, s2, v144
	v_mov_b32_e32 v197, 0
	v_lshlrev_b64 v[196:197], 6, v[196:197]
	v_lshl_add_u64 v[196:197], s[46:47], 0, v[196:197]
	v_lshl_add_u64 v[196:197], v[196:197], 0, v[158:159]
	global_store_dwordx4 v[196:197], v[48:51], off
	v_add_u32_e32 v196, s2, v145
	v_mov_b32_e32 v197, 0
	v_lshlrev_b64 v[196:197], 6, v[196:197]
	v_lshl_add_u64 v[196:197], s[46:47], 0, v[196:197]
	v_lshl_add_u64 v[196:197], v[196:197], 0, v[158:159]
	global_store_dwordx4 v[196:197], v[32:35], off
	v_add_u32_e32 v196, s2, v146
	v_mov_b32_e32 v197, 0
	v_lshlrev_b64 v[196:197], 6, v[196:197]
	v_lshl_add_u64 v[196:197], s[46:47], 0, v[196:197]
	v_lshl_add_u64 v[196:197], v[196:197], 0, v[158:159]
	global_store_dwordx4 v[196:197], v[16:19], off
	v_add_u32_e32 v196, s2, v147
	v_mov_b32_e32 v197, 0
	v_lshlrev_b64 v[196:197], 6, v[196:197]
	v_lshl_add_u64 v[196:197], s[46:47], 0, v[196:197]
	v_lshl_add_u64 v[196:197], v[196:197], 0, v[158:159]
	global_store_dwordx4 v[196:197], v[4:7], off
.Le1_nogate:
	s_and_b64 vcc, exec, s[40:41]
	s_mov_b32 s42, s48
	s_mov_b32 s4, s50
	s_mov_b64 s[8:9], s[54:55]
	s_mov_b64 s[6:7], s[52:53]
	s_cbranch_vccnz .LBB0_816
	s_branch .LBB0_792
